# v9: RG-LRU scan skips identity steps for sample units + M3 GLA items re-assigned accordingly; on top of v7
# speedup vs baseline: 1.0365x; 1.0026x over previous
; #define LBAR() do { asm volatile("s_waitcnt lgkmcnt(0)" ::: "memory"); __builtin_amdgcn_s_barrier(); asm volatile("" ::: "memory"); } while (0)
; DI KA get_ka() { KA p = (KA)__builtin_amdgcn_kernarg_segment_ptr(); asm volatile("" : "+s"(p)); return p; }
; __global__ void __launch_bounds__(512, 2) hymba_fwd(Args a_unused) {
;     ...
;         for (int it = blockIdx.x; it < NUNIT + 2 * NUNIT; it += gridDim.x) {
;             if (it < NUNIT) { lru_unit<true>(get_ka(), l, it, lds); LBAR(); }
;             else { for (int rep = 0; rep < REP_M3G; ++rep) gla_unit<true>(get_ka(), l, it - NUNIT, lds); }
;         }
.Lm3_first_gla:
	s_cmpk_lt_i32 s2, 0x88
	s_cselect_b32 s3, 0, 0xa8
	s_add_i32 s62, s2, s3
	s_addk_i32 s62, 0x188
	s_branch .LBB0_792
.Lm3_adv_gla:
	s_sub_i32 s3, s62, 0x188
	s_cmpk_lt_i32 s2, 8
	s_cbranch_scc1 .LBB0_1057
	s_cmpk_lt_i32 s2, 0x88
	s_cbranch_scc0 .Lm3_adv_c
	s_cmpk_lt_i32 s3, 0x88
	s_cbranch_scc1 .Lm3_adv_b128
	s_cmpk_lt_i32 s3, 0x108
	s_cbranch_scc0 .LBB0_1057
	s_cmpk_lt_i32 s2, 48
	s_cbranch_scc0 .LBB0_1057
.Lm3_adv_b128:
	s_addk_i32 s62, 0x80
	s_branch .LBB0_792
.Lm3_adv_c:
	s_sub_i32 s4, s3, 0x130
	s_cmpk_lt_i32 s4, 0x168
	s_cbranch_scc0 .LBB0_1057
	s_addk_i32 s62, 0x78
	s_branch .LBB0_792

; DI float bf2f(unsigned v) { return __uint_as_float(v << 16); }
; DI float sigmoidf_(float x) { return rcpf(1.f + __expf(-x)); }
; template <bool FINAL>
; DI void lru_unit(KA a, int l, int unit, LAS unsigned char* lds) {
;     ...
;         const int cl = 32 * nb + r, chn = 64 * w + cl;
;         const float ba_ = a->in[14][l * DLRU + chn], bx_ = a->in[16][l * DLRU + chn];
;         const float c8 = -8.f * log1pf(__expf(-a->in[17][l * DLRU + chn]));
;         float cin = 0.f;
;         if (FINAL && !u.prompt) cin = a->in[2][(size_t)(l * NSB + u.s) * DLRU + chn];
; #pragma unroll
;         for (int mb = 0; mb < 2; ++mb) {
;             float pp = 1.f, hh = 0.f;
; #pragma unroll
;             for (int i = 0; i < 16; ++i) {
;                 const int t = 32 * mb + 16 * h + i;
;                 const float rg = sigmoidf_(ar[mb][i] + ba_), ig = sigmoidf_(ai[mb][i] + bx_);
;                 const float la = c8 * rg;
;                 float av = __expf(la), mult = __builtin_amdgcn_sqrtf(fmaxf(1.f - av * av, 0.f));
;                 const float xcv = bf2f(xc[t * 72 + cl]);
;                 float bt = mult * ig * xcv;
;                 if (u.prompt && u.c == 0 && t == 0) { av = 0.f; bt = ig * xcv; }
;                 if (t >= nvalid) { av = 1.f; bt = 0.f; }
;                 hh = av * hh + bt; pp *= av;
;                 ar[mb][i] = pp; ai[mb][i] = hh;
;             }
.LBB0_1015:
	s_waitcnt vmcnt(0)
	v_mul_f32_e32 v178, 0xbfb8aa3b, v178
	v_exp_f32_e32 v178, v178
	s_mov_b32 s4, 0x3f2aaaab
	v_add_f32_e32 v48, v48, v177
	v_mul_f32_e32 v48, 0xbfb8aa3b, v48
	v_add_f32_e32 v182, 1.0, v178
	v_frexp_mant_f32_e32 v184, v182
	v_cvt_f64_f32_e32 v[180:181], v182
	v_add_f32_e32 v183, -1.0, v182
	v_frexp_exp_i32_f64_e32 v180, v[180:181]
	v_cmp_gt_f32_e32 vcc, s4, v184
	v_sub_f32_e32 v185, v183, v182
	v_sub_f32_e32 v183, v178, v183
	v_subbrev_co_u32_e32 v180, vcc, 0, v180, vcc
	v_add_f32_e32 v185, 1.0, v185
	v_sub_u32_e32 v181, 0, v180
	v_add_f32_e32 v183, v183, v185
	v_ldexp_f32 v182, v182, v181
	v_ldexp_f32 v181, v183, v181
	v_add_f32_e32 v183, -1.0, v182
	v_add_f32_e32 v186, 1.0, v182
	v_add_f32_e32 v184, 1.0, v183
	v_add_f32_e32 v187, -1.0, v186
	v_sub_f32_e32 v184, v182, v184
	v_sub_f32_e32 v182, v182, v187
	v_add_f32_e32 v184, v181, v184
	v_add_f32_e32 v181, v181, v182
	v_add_f32_e32 v182, v186, v181
	v_rcp_f32_e32 v187, v182
	v_add_f32_e32 v185, v183, v184
	v_sub_f32_e32 v183, v185, v183
	v_sub_f32_e32 v183, v184, v183
	v_sub_f32_e32 v184, v182, v186
	v_sub_f32_e32 v181, v181, v184
	v_mul_f32_e32 v184, v185, v187
	v_mul_f32_e32 v186, v182, v184
	v_fma_f32 v188, v184, v182, -v186
	v_fmac_f32_e32 v188, v184, v181
	v_add_f32_e32 v189, v186, v188
	v_sub_f32_e32 v190, v185, v189
	v_sub_f32_e32 v185, v185, v190
	v_sub_f32_e32 v186, v189, v186
	v_sub_f32_e32 v185, v185, v189
	v_add_f32_e32 v183, v183, v185
	v_sub_f32_e32 v185, v186, v188
	v_add_f32_e32 v183, v185, v183
	v_add_f32_e32 v185, v190, v183
	v_mul_f32_e32 v186, v187, v185
	v_mul_f32_e32 v188, v182, v186
	v_fma_f32 v182, v186, v182, -v188
	v_fmac_f32_e32 v182, v186, v181
	v_sub_f32_e32 v181, v190, v185
	v_add_f32_e32 v181, v183, v181
	v_add_f32_e32 v183, v188, v182
	v_sub_f32_e32 v189, v185, v183
	v_sub_f32_e32 v185, v185, v189
	v_sub_f32_e32 v188, v183, v188
	v_sub_f32_e32 v183, v185, v183
	v_add_f32_e32 v181, v181, v183
	v_sub_f32_e32 v182, v188, v182
	v_cvt_f32_i32_e32 v180, v180
	v_add_f32_e32 v181, v182, v181
	v_add_f32_e32 v182, v184, v186
	v_add_f32_e32 v181, v189, v181
	v_sub_f32_e32 v183, v182, v184
	v_mul_f32_e32 v181, v187, v181
	v_sub_f32_e32 v183, v186, v183
	v_add_f32_e32 v181, v183, v181
	v_mul_f32_e32 v186, 0x3f317218, v180
	s_mov_b32 s4, 0x3f317218
	v_add_f32_e32 v183, v182, v181
	v_fma_f32 v187, v180, s4, -v186
	v_mul_f32_e32 v184, v183, v183
	v_mov_b32_e32 v185, 0x3ecc95a3
	v_fmac_f32_e32 v187, 0xb102e308, v180
	v_sub_f32_e32 v180, v183, v182
	v_fmamk_f32 v185, v184, 0x3e9b6dac, v185
	v_sub_f32_e32 v180, v181, v180
	v_add_f32_e32 v181, v186, v187
	v_fmaak_f32 v185, v184, v185, 0x3f2aaada
	v_sub_f32_e32 v182, v181, v186
	v_ldexp_f32 v186, v183, 1
	v_mul_f32_e32 v183, v183, v184
	v_mul_f32_e32 v183, v183, v185
	v_add_f32_e32 v184, v186, v183
	v_sub_f32_e32 v185, v184, v186
	v_ldexp_f32 v180, v180, 1
	v_sub_f32_e32 v183, v183, v185
	v_add_f32_e32 v180, v180, v183
	v_add_f32_e32 v183, v184, v180
	v_sub_f32_e32 v184, v183, v184
	v_sub_f32_e32 v180, v180, v184
	v_add_f32_e32 v184, v181, v183
	v_sub_f32_e32 v185, v184, v181
	v_sub_f32_e32 v186, v184, v185
	v_sub_f32_e32 v182, v187, v182
	v_sub_f32_e32 v181, v181, v186
	v_sub_f32_e32 v183, v183, v185
	v_add_f32_e32 v181, v183, v181
	v_add_f32_e32 v183, v182, v180
	v_sub_f32_e32 v185, v183, v182
	v_sub_f32_e32 v186, v183, v185
	v_sub_f32_e32 v182, v182, v186
	v_sub_f32_e32 v180, v180, v185
	v_add_f32_e32 v181, v183, v181
	v_add_f32_e32 v180, v180, v182
	v_add_f32_e32 v182, v184, v181
	v_sub_f32_e32 v183, v182, v184
	v_exp_f32_e32 v48, v48
	v_sub_f32_e32 v181, v181, v183
	v_add_f32_e32 v180, v180, v181
	s_mov_b32 s4, 0x7f800000
	v_add_f32_e32 v180, v182, v180
	v_cmp_neq_f32_e32 vcc, s4, v178
	v_add_f32_e32 v48, 1.0, v48
	s_mov_b32 s4, 0x33800000
	v_cndmask_b32_e32 v180, v230, v180, vcc
	v_cmp_ngt_f32_e32 vcc, -1.0, v178
	v_rcp_f32_e32 v48, v48
	v_add_f32_e32 v49, v49, v177
	v_cndmask_b32_e32 v180, v231, v180, vcc
	v_cmp_neq_f32_e32 vcc, -1.0, v178
	v_mul_f32_e32 v49, 0xbfb8aa3b, v49
	v_exp_f32_e32 v49, v49
	v_cndmask_b32_e32 v180, v232, v180, vcc
	v_cmp_lt_f32_e64 vcc, |v178|, s4
	v_add_f32_e32 v32, v32, v176
	v_mul_f32_e32 v32, 0xbfb8aa3b, v32
	v_cndmask_b32_e32 v178, v180, v178, vcc
	v_mul_f32_e32 v178, 0xc1000000, v178
	v_mul_f32_e32 v48, v48, v178
	v_mul_f32_e32 v48, 0x3fb8aa3b, v48
	v_exp_f32_e32 v48, v48
	v_add_f32_e32 v49, 1.0, v49
	v_exp_f32_e32 v32, v32
	v_rcp_f32_e32 v49, v49
	v_fma_f32 v180, -v48, v48, 1.0
	v_add_f32_e32 v33, v33, v176
	v_add_f32_e32 v32, 1.0, v32
	v_max_f32_e32 v180, 0, v180
	v_mul_f32_e32 v33, 0xbfb8aa3b, v33
	v_mul_f32_e32 v49, v49, v178
	v_rcp_f32_e32 v32, v32
	v_sqrt_f32_e32 v180, v180
	v_exp_f32_e32 v33, v33
	v_mul_f32_e32 v49, 0x3fb8aa3b, v49
	v_exp_f32_e32 v49, v49
	v_add_f32_e32 v50, v50, v177
	v_mul_f32_e32 v50, 0xbfb8aa3b, v50
	v_lshl_add_u32 v179, v179, 1, s95
	v_exp_f32_e32 v50, v50
	v_add_u32_e32 v181, v179, v127
	v_mul_f32_e32 v180, v32, v180
	v_add_f32_e32 v33, 1.0, v33
	v_add_u32_e32 v179, v179, v128
	ds_read_u16 v181, v181
	ds_read_u16 v182, v179
	ds_read_u16 v183, v179 offset:144
	ds_read_u16 v184, v179 offset:288
	ds_read_u16 v185, v179 offset:432
	ds_read_u16 v186, v179 offset:576
	ds_read_u16 v187, v179 offset:720
	ds_read_u16 v188, v179 offset:864
	v_cndmask_b32_e64 v32, v180, v32, s[22:23]
	v_rcp_f32_e32 v180, v33
	v_fma_f32 v33, -v49, v49, 1.0
	s_waitcnt lgkmcnt(7)
	v_lshlrev_b32_e32 v181, 16, v181
	v_max_f32_e32 v33, 0, v33
	v_mul_f32_e32 v32, v32, v181
	v_sqrt_f32_e32 v181, v33
	v_add_f32_e32 v50, 1.0, v50
	v_add_f32_e32 v51, v51, v177
	v_rcp_f32_e32 v50, v50
	v_mul_f32_e32 v51, 0xbfb8aa3b, v51
	v_exp_f32_e32 v51, v51
	v_cndmask_b32_e64 v48, v48, 0, s[22:23]
	v_add_f32_e32 v34, v34, v176
	v_cndmask_b32_e64 v33, 1.0, v48, s[24:25]
	s_waitcnt lgkmcnt(6)
; DI float bf2f(unsigned v) { return __uint_as_float(v << 16); }
; DI float sigmoidf_(float x) { return rcpf(1.f + __expf(-x)); }
; template <bool FINAL>
; DI void lru_unit(KA a, int l, int unit, LAS unsigned char* lds) {
;     ...
; #pragma unroll
;         for (int mb = 0; mb < 2; ++mb) {
;             float pp = 1.f, hh = 0.f;
; #pragma unroll
;             for (int i = 0; i < 16; ++i) {
;                 const int t = 32 * mb + 16 * h + i;
;                 const float rg = sigmoidf_(ar[mb][i] + ba_), ig = sigmoidf_(ai[mb][i] + bx_);
;                 const float la = c8 * rg;
;                 float av = __expf(la), mult = __builtin_amdgcn_sqrtf(fmaxf(1.f - av * av, 0.f));
;                 const float xcv = bf2f(xc[t * 72 + cl]);
;                 float bt = mult * ig * xcv;
;                 if (u.prompt && u.c == 0 && t == 0) { av = 0.f; bt = ig * xcv; }
;                 if (t >= nvalid) { av = 1.f; bt = 0.f; }
;                 hh = av * hh + bt; pp *= av;
;                 ar[mb][i] = pp; ai[mb][i] = hh;
;             }
	v_lshlrev_b32_e32 v48, 16, v182
	v_mul_f32_e32 v180, v180, v181
	v_mul_f32_e32 v34, 0xbfb8aa3b, v34
	v_mul_f32_e32 v48, v180, v48
	v_exp_f32_e32 v180, v34
	v_mul_f32_e32 v34, v50, v178
	v_mul_f32_e32 v34, 0x3fb8aa3b, v34
	v_add_f32_e32 v51, 1.0, v51
	v_exp_f32_e32 v50, v34
	v_rcp_f32_e32 v51, v51
	v_cndmask_b32_e64 v32, 0, v32, s[24:25]
	v_fmac_f32_e32 v32, 0, v33
	v_cndmask_b32_e64 v48, 0, v48, s[26:27]
	v_cndmask_b32_e64 v49, 1.0, v49, s[26:27]
	v_add_f32_e32 v35, v35, v176
	v_fmac_f32_e32 v48, v49, v32
	v_mul_f32_e32 v34, v49, v33
	v_add_f32_e32 v49, 1.0, v180
	v_fma_f32 v180, -v50, v50, 1.0
	v_mul_f32_e32 v35, 0xbfb8aa3b, v35
	v_mul_f32_e32 v51, v51, v178
	v_max_f32_e32 v180, 0, v180
	v_exp_f32_e32 v35, v35
	v_mul_f32_e32 v51, 0x3fb8aa3b, v51
	v_rcp_f32_e32 v49, v49
	v_sqrt_f32_e32 v180, v180
	v_exp_f32_e32 v51, v51
	v_add_f32_e32 v52, v52, v177
	v_mul_f32_e32 v52, 0xbfb8aa3b, v52
	v_exp_f32_e32 v52, v52
	v_add_f32_e32 v35, 1.0, v35
	v_mul_f32_e32 v49, v49, v180
	v_rcp_f32_e32 v180, v35
	v_fma_f32 v35, -v51, v51, 1.0
	s_waitcnt lgkmcnt(5)
	v_lshlrev_b32_e32 v181, 16, v183
	v_max_f32_e32 v35, 0, v35
	v_mul_f32_e32 v49, v49, v181
	v_sqrt_f32_e32 v181, v35
	v_add_f32_e32 v52, 1.0, v52
	v_add_f32_e32 v53, v53, v177
	v_rcp_f32_e32 v52, v52
	v_mul_f32_e32 v53, 0xbfb8aa3b, v53
	v_exp_f32_e32 v53, v53
	v_cndmask_b32_e64 v49, 0, v49, s[28:29]
	v_cndmask_b32_e64 v50, 1.0, v50, s[28:29]
	v_add_f32_e32 v36, v36, v176
	v_fmac_f32_e32 v49, v50, v48
	v_mul_f32_e32 v35, v50, v34
	s_waitcnt lgkmcnt(4)
	v_lshlrev_b32_e32 v50, 16, v184
	v_mul_f32_e32 v180, v180, v181
	v_mul_f32_e32 v36, 0xbfb8aa3b, v36
	v_mul_f32_e32 v50, v180, v50
	v_exp_f32_e32 v180, v36
	v_mul_f32_e32 v36, v52, v178
	v_mul_f32_e32 v36, 0x3fb8aa3b, v36
	v_add_f32_e32 v53, 1.0, v53
	v_exp_f32_e32 v52, v36
	v_rcp_f32_e32 v53, v53
	v_cndmask_b32_e64 v50, 0, v50, s[30:31]
	v_cndmask_b32_e64 v51, 1.0, v51, s[30:31]
	v_add_f32_e32 v37, v37, v176
	v_fmac_f32_e32 v50, v51, v49
	v_mul_f32_e32 v36, v51, v35
	v_add_f32_e32 v51, 1.0, v180
	v_fma_f32 v180, -v52, v52, 1.0
	v_mul_f32_e32 v37, 0xbfb8aa3b, v37
	v_mul_f32_e32 v53, v53, v178
	v_max_f32_e32 v180, 0, v180
	v_exp_f32_e32 v37, v37
	v_mul_f32_e32 v53, 0x3fb8aa3b, v53
	v_rcp_f32_e32 v51, v51
	v_sqrt_f32_e32 v180, v180
	v_exp_f32_e32 v53, v53
	v_add_f32_e32 v54, v54, v177
	v_mul_f32_e32 v54, 0xbfb8aa3b, v54
	v_exp_f32_e32 v54, v54
	v_add_f32_e32 v37, 1.0, v37
	v_mul_f32_e32 v51, v51, v180
	v_rcp_f32_e32 v180, v37
	v_fma_f32 v37, -v53, v53, 1.0
	s_waitcnt lgkmcnt(3)
	v_lshlrev_b32_e32 v181, 16, v185
	v_max_f32_e32 v37, 0, v37
	v_mul_f32_e32 v51, v51, v181
	v_sqrt_f32_e32 v181, v37
	v_add_f32_e32 v54, 1.0, v54
	v_add_f32_e32 v55, v55, v177
	v_rcp_f32_e32 v54, v54
	v_mul_f32_e32 v55, 0xbfb8aa3b, v55
	v_exp_f32_e32 v55, v55
	v_cndmask_b32_e64 v51, 0, v51, s[34:35]
	v_cndmask_b32_e64 v52, 1.0, v52, s[34:35]
	v_add_f32_e32 v38, v38, v176
	v_fmac_f32_e32 v51, v52, v50
	v_mul_f32_e32 v37, v52, v36
	s_waitcnt lgkmcnt(2)
	v_lshlrev_b32_e32 v52, 16, v186
	v_mul_f32_e32 v180, v180, v181
	v_mul_f32_e32 v38, 0xbfb8aa3b, v38
	v_mul_f32_e32 v52, v180, v52
	v_exp_f32_e32 v180, v38
	v_mul_f32_e32 v38, v54, v178
	v_mul_f32_e32 v38, 0x3fb8aa3b, v38
	v_add_f32_e32 v55, 1.0, v55
	v_exp_f32_e32 v54, v38
	v_rcp_f32_e32 v55, v55
	v_cndmask_b32_e64 v52, 0, v52, s[36:37]
	v_cndmask_b32_e64 v53, 1.0, v53, s[36:37]
	v_add_f32_e32 v39, v39, v176
	v_fmac_f32_e32 v52, v53, v51
	v_mul_f32_e32 v38, v53, v37
	v_add_f32_e32 v53, 1.0, v180
	v_fma_f32 v180, -v54, v54, 1.0
	v_mul_f32_e32 v39, 0xbfb8aa3b, v39
	v_mul_f32_e32 v55, v55, v178
	v_max_f32_e32 v180, 0, v180
	v_exp_f32_e32 v39, v39
	v_mul_f32_e32 v55, 0x3fb8aa3b, v55
	v_rcp_f32_e32 v53, v53
	v_sqrt_f32_e32 v180, v180
	v_exp_f32_e32 v55, v55
	v_add_f32_e32 v56, v56, v177
	v_mul_f32_e32 v56, 0xbfb8aa3b, v56
	v_exp_f32_e32 v56, v56
	v_add_f32_e32 v39, 1.0, v39
	v_mul_f32_e32 v53, v53, v180
	v_rcp_f32_e32 v180, v39
	v_fma_f32 v39, -v55, v55, 1.0
	s_waitcnt lgkmcnt(1)
	v_lshlrev_b32_e32 v181, 16, v187
	v_max_f32_e32 v39, 0, v39
	v_mul_f32_e32 v53, v53, v181
	v_sqrt_f32_e32 v181, v39
	v_add_f32_e32 v56, 1.0, v56
	v_add_f32_e32 v57, v57, v177
	v_rcp_f32_e32 v56, v56
	v_mul_f32_e32 v57, 0xbfb8aa3b, v57
	v_exp_f32_e32 v57, v57
	v_cndmask_b32_e64 v53, 0, v53, s[38:39]
	v_cndmask_b32_e64 v54, 1.0, v54, s[38:39]
	v_add_f32_e32 v40, v40, v176
	v_fmac_f32_e32 v53, v54, v52
	v_mul_f32_e32 v39, v54, v38
	s_waitcnt lgkmcnt(0)
	v_lshlrev_b32_e32 v54, 16, v188
	v_mul_f32_e32 v180, v180, v181
	v_mul_f32_e32 v40, 0xbfb8aa3b, v40
	v_mul_f32_e32 v54, v180, v54
	v_exp_f32_e32 v180, v40
	v_mul_f32_e32 v40, v56, v178
	v_mul_f32_e32 v40, 0x3fb8aa3b, v40
	v_add_f32_e32 v57, 1.0, v57
	v_exp_f32_e32 v56, v40
	v_rcp_f32_e32 v57, v57
	v_cndmask_b32_e64 v54, 0, v54, s[40:41]
	v_cndmask_b32_e64 v55, 1.0, v55, s[40:41]
	v_add_f32_e32 v41, v41, v176
	v_fmac_f32_e32 v54, v55, v53
	v_mul_f32_e32 v40, v55, v39
	v_readlane_b32 s4, v255, 14
	v_readlane_b32 s5, v255, 15
	s_and_b64 vcc, exec, s[4:5]
	s_cbranch_vccnz .Llru_scan_cont
	s_waitcnt lgkmcnt(0)
	v_mov_b32_e32 v55, v54
	v_mov_b32_e32 v41, v40
	v_mov_b32_e32 v56, v54
	v_mov_b32_e32 v42, v40
	v_mov_b32_e32 v57, v54
	v_mov_b32_e32 v43, v40
	v_mov_b32_e32 v58, v54
	v_mov_b32_e32 v44, v40
	v_mov_b32_e32 v59, v54
	v_mov_b32_e32 v45, v40
	v_mov_b32_e32 v60, v54
	v_mov_b32_e32 v46, v40
	v_mov_b32_e32 v61, v54
	v_mov_b32_e32 v47, v40
	v_mov_b32_e32 v62, v54
	v_mov_b32_e32 v63, v40
	v_mov_b32_e32 v180, 0
	v_mov_b32_e32 v181, 1.0
	v_mov_b32_e32 v18, 0
	v_mov_b32_e32 v182, 1.0
	v_mov_b32_e32 v19, 0
	v_mov_b32_e32 v183, 1.0
	v_mov_b32_e32 v20, 0
	v_mov_b32_e32 v184, 1.0
	v_mov_b32_e32 v21, 0
	v_mov_b32_e32 v185, 1.0
	v_mov_b32_e32 v22, 0
	v_mov_b32_e32 v186, 1.0
	v_mov_b32_e32 v23, 0
	v_mov_b32_e32 v187, 1.0
	v_mov_b32_e32 v24, 0
	v_mov_b32_e32 v188, 1.0
	v_mov_b32_e32 v25, 0
	v_mov_b32_e32 v179, 1.0
	v_mov_b32_e32 v26, 0
	v_mov_b32_e32 v189, 1.0
	v_mov_b32_e32 v27, 0
	v_mov_b32_e32 v190, 1.0
	v_mov_b32_e32 v28, 0
	v_mov_b32_e32 v191, 1.0
	v_mov_b32_e32 v29, 0
	v_mov_b32_e32 v192, 1.0
	v_mov_b32_e32 v30, 0
	v_mov_b32_e32 v193, 1.0
	v_mov_b32_e32 v31, 0
	v_mov_b32_e32 v176, 1.0
	v_mov_b32_e32 v177, 0
	v_mov_b32_e32 v178, 1.0
	s_branch .Llru_scan_end
; DI float bf2f(unsigned v) { return __uint_as_float(v << 16); }
; DI float sigmoidf_(float x) { return rcpf(1.f + __expf(-x)); }
; template <bool FINAL>
; DI void lru_unit(KA a, int l, int unit, LAS unsigned char* lds) {
;     ...
; #pragma unroll
;         for (int mb = 0; mb < 2; ++mb) {
;             float pp = 1.f, hh = 0.f;
; #pragma unroll
;             for (int i = 0; i < 16; ++i) {
;                 const int t = 32 * mb + 16 * h + i;
;                 const float rg = sigmoidf_(ar[mb][i] + ba_), ig = sigmoidf_(ai[mb][i] + bx_);
;                 const float la = c8 * rg;
;                 float av = __expf(la), mult = __builtin_amdgcn_sqrtf(fmaxf(1.f - av * av, 0.f));
;                 const float xcv = bf2f(xc[t * 72 + cl]);
;                 float bt = mult * ig * xcv;
;                 if (u.prompt && u.c == 0 && t == 0) { av = 0.f; bt = ig * xcv; }
;                 if (t >= nvalid) { av = 1.f; bt = 0.f; }
;                 hh = av * hh + bt; pp *= av;
;                 ar[mb][i] = pp; ai[mb][i] = hh;
;             }
.Llru_scan_cont:
	v_add_f32_e32 v55, 1.0, v180
	v_fma_f32 v180, -v56, v56, 1.0
	v_mul_f32_e32 v41, 0xbfb8aa3b, v41
	v_mul_f32_e32 v57, v57, v178
	v_max_f32_e32 v180, 0, v180
	v_exp_f32_e32 v41, v41
	v_mul_f32_e32 v57, 0x3fb8aa3b, v57
	v_rcp_f32_e32 v55, v55
	v_sqrt_f32_e32 v180, v180
	v_exp_f32_e32 v57, v57
	v_add_f32_e32 v58, v58, v177
	v_mul_f32_e32 v58, 0xbfb8aa3b, v58
	v_exp_f32_e32 v58, v58
	v_add_f32_e32 v41, 1.0, v41
	ds_read_u16 v181, v179 offset:1008
	ds_read_u16 v182, v179 offset:1152
	ds_read_u16 v183, v179 offset:1296
	ds_read_u16 v184, v179 offset:1440
	ds_read_u16 v185, v179 offset:1584
	ds_read_u16 v186, v179 offset:1728
	ds_read_u16 v187, v179 offset:1872
	ds_read_u16 v188, v179 offset:2016
	v_mul_f32_e32 v55, v55, v180
	v_rcp_f32_e32 v180, v41
	v_fma_f32 v41, -v57, v57, 1.0
	s_waitcnt lgkmcnt(7)
	v_lshlrev_b32_e32 v181, 16, v181
	v_max_f32_e32 v41, 0, v41
	v_mul_f32_e32 v55, v55, v181
	v_sqrt_f32_e32 v181, v41
	v_add_f32_e32 v58, 1.0, v58
	v_add_f32_e32 v59, v59, v177
	v_rcp_f32_e32 v58, v58
	v_mul_f32_e32 v59, 0xbfb8aa3b, v59
	v_exp_f32_e32 v59, v59
	v_cndmask_b32_e64 v55, 0, v55, s[42:43]
	v_cndmask_b32_e64 v56, 1.0, v56, s[42:43]
	v_add_f32_e32 v42, v42, v176
	v_fmac_f32_e32 v55, v56, v54
	v_mul_f32_e32 v41, v56, v40
	s_waitcnt lgkmcnt(6)
	v_lshlrev_b32_e32 v56, 16, v182
	v_mul_f32_e32 v180, v180, v181
	v_mul_f32_e32 v42, 0xbfb8aa3b, v42
	v_mul_f32_e32 v56, v180, v56
	v_exp_f32_e32 v180, v42
	v_mul_f32_e32 v42, v58, v178
	v_mul_f32_e32 v42, 0x3fb8aa3b, v42
	v_add_f32_e32 v59, 1.0, v59
	v_exp_f32_e32 v58, v42
	v_rcp_f32_e32 v59, v59
	v_cndmask_b32_e64 v56, 0, v56, s[44:45]
	v_cndmask_b32_e64 v57, 1.0, v57, s[44:45]
	v_add_f32_e32 v43, v43, v176
	v_fmac_f32_e32 v56, v57, v55
	v_mul_f32_e32 v42, v57, v41
	v_add_f32_e32 v57, 1.0, v180
	v_fma_f32 v180, -v58, v58, 1.0
	v_mul_f32_e32 v43, 0xbfb8aa3b, v43
	v_mul_f32_e32 v59, v59, v178
	v_max_f32_e32 v180, 0, v180
	v_exp_f32_e32 v43, v43
	v_mul_f32_e32 v59, 0x3fb8aa3b, v59
	v_rcp_f32_e32 v57, v57
	v_sqrt_f32_e32 v180, v180
	v_exp_f32_e32 v59, v59
	v_add_f32_e32 v60, v60, v177
	v_mul_f32_e32 v60, 0xbfb8aa3b, v60
	v_exp_f32_e32 v60, v60
	v_add_f32_e32 v43, 1.0, v43
	v_mul_f32_e32 v57, v57, v180
	v_rcp_f32_e32 v180, v43
	v_fma_f32 v43, -v59, v59, 1.0
	s_waitcnt lgkmcnt(5)
	v_lshlrev_b32_e32 v181, 16, v183
	v_max_f32_e32 v43, 0, v43
	v_mul_f32_e32 v57, v57, v181
	v_sqrt_f32_e32 v181, v43
	v_add_f32_e32 v60, 1.0, v60
	v_add_f32_e32 v61, v61, v177
	v_rcp_f32_e32 v60, v60
	v_mul_f32_e32 v61, 0xbfb8aa3b, v61
	v_exp_f32_e32 v61, v61
	v_cndmask_b32_e64 v57, 0, v57, s[46:47]
	v_cndmask_b32_e64 v58, 1.0, v58, s[46:47]
	v_add_f32_e32 v44, v44, v176
	v_fmac_f32_e32 v57, v58, v56
	v_mul_f32_e32 v43, v58, v42
	s_waitcnt lgkmcnt(4)
	v_lshlrev_b32_e32 v58, 16, v184
	v_mul_f32_e32 v180, v180, v181
	v_mul_f32_e32 v44, 0xbfb8aa3b, v44
	v_mul_f32_e32 v58, v180, v58
	v_exp_f32_e32 v180, v44
	v_mul_f32_e32 v44, v60, v178
	v_mul_f32_e32 v44, 0x3fb8aa3b, v44
	v_add_f32_e32 v61, 1.0, v61
	v_exp_f32_e32 v60, v44
	v_rcp_f32_e32 v61, v61
	v_cndmask_b32_e64 v58, 0, v58, s[48:49]
	v_cndmask_b32_e64 v59, 1.0, v59, s[48:49]
	v_add_f32_e32 v45, v45, v176
	v_fmac_f32_e32 v58, v59, v57
	v_mul_f32_e32 v44, v59, v43
	v_add_f32_e32 v59, 1.0, v180
	v_fma_f32 v180, -v60, v60, 1.0
	v_mul_f32_e32 v45, 0xbfb8aa3b, v45
	v_mul_f32_e32 v61, v61, v178
	v_max_f32_e32 v180, 0, v180
	v_exp_f32_e32 v45, v45
	v_mul_f32_e32 v61, 0x3fb8aa3b, v61
	v_rcp_f32_e32 v59, v59
	v_sqrt_f32_e32 v180, v180
	v_exp_f32_e32 v61, v61
	v_add_f32_e32 v62, v62, v177
	v_mul_f32_e32 v62, 0xbfb8aa3b, v62
	v_exp_f32_e32 v62, v62
	v_add_f32_e32 v45, 1.0, v45
	v_mul_f32_e32 v59, v59, v180
	v_rcp_f32_e32 v180, v45
	v_fma_f32 v45, -v61, v61, 1.0
	s_waitcnt lgkmcnt(3)
	v_lshlrev_b32_e32 v181, 16, v185
	v_max_f32_e32 v45, 0, v45
	v_mul_f32_e32 v59, v59, v181
	v_sqrt_f32_e32 v181, v45
	v_add_f32_e32 v62, 1.0, v62
	v_add_f32_e32 v63, v63, v177
	v_rcp_f32_e32 v62, v62
	v_mul_f32_e32 v63, 0xbfb8aa3b, v63
	v_exp_f32_e32 v63, v63
	v_cndmask_b32_e64 v59, 0, v59, s[50:51]
	v_cndmask_b32_e64 v60, 1.0, v60, s[50:51]
	v_add_f32_e32 v46, v46, v176
	v_fmac_f32_e32 v59, v60, v58
	v_mul_f32_e32 v45, v60, v44
	s_waitcnt lgkmcnt(2)
	v_lshlrev_b32_e32 v60, 16, v186
	v_mul_f32_e32 v180, v180, v181
	v_mul_f32_e32 v46, 0xbfb8aa3b, v46
	v_mul_f32_e32 v60, v180, v60
	v_exp_f32_e32 v180, v46
	v_mul_f32_e32 v46, v62, v178
	v_mul_f32_e32 v46, 0x3fb8aa3b, v46
	v_add_f32_e32 v63, 1.0, v63
	v_exp_f32_e32 v62, v46
	v_rcp_f32_e32 v63, v63
	v_add_f32_e32 v16, v16, v177
	v_mul_f32_e32 v16, 0xbfb8aa3b, v16
	v_exp_f32_e32 v16, v16
	v_cndmask_b32_e64 v60, 0, v60, s[52:53]
	v_cndmask_b32_e64 v61, 1.0, v61, s[52:53]
	v_add_f32_e32 v47, v47, v176
	v_fmac_f32_e32 v60, v61, v59
	v_mul_f32_e32 v46, v61, v45
	v_add_f32_e32 v61, 1.0, v180
	v_fma_f32 v180, -v62, v62, 1.0
	v_mul_f32_e32 v47, 0xbfb8aa3b, v47
	v_mul_f32_e32 v63, v63, v178
	v_max_f32_e32 v180, 0, v180
	v_exp_f32_e32 v47, v47
	v_mul_f32_e32 v63, 0x3fb8aa3b, v63
	v_rcp_f32_e32 v61, v61
	v_sqrt_f32_e32 v180, v180
	v_exp_f32_e32 v63, v63
	v_add_f32_e32 v16, 1.0, v16
	v_rcp_f32_e32 v16, v16
	v_add_f32_e32 v17, v17, v177
	v_add_f32_e32 v47, 1.0, v47
	v_mul_f32_e32 v17, 0xbfb8aa3b, v17
	v_mul_f32_e32 v61, v61, v180
	v_rcp_f32_e32 v180, v47
	v_fma_f32 v47, -v63, v63, 1.0
	v_exp_f32_e32 v17, v17
	s_waitcnt lgkmcnt(1)
	v_lshlrev_b32_e32 v181, 16, v187
	v_max_f32_e32 v47, 0, v47
	v_mul_f32_e32 v16, v16, v178
	v_mul_f32_e32 v61, v61, v181
	v_sqrt_f32_e32 v181, v47
	v_add_f32_e32 v0, v0, v176
	v_mul_f32_e32 v16, 0x3fb8aa3b, v16
	v_mul_f32_e32 v0, 0xbfb8aa3b, v0
	v_exp_f32_e32 v16, v16
	v_exp_f32_e32 v0, v0
	v_add_f32_e32 v17, 1.0, v17
	v_cndmask_b32_e64 v61, 0, v61, s[54:55]
	v_cndmask_b32_e64 v62, 1.0, v62, s[54:55]
	v_rcp_f32_e32 v17, v17
	v_fmac_f32_e32 v61, v62, v60
	v_mul_f32_e32 v47, v62, v46
	s_waitcnt lgkmcnt(0)
; DI float bf2f(unsigned v) { return __uint_as_float(v << 16); }
; DI float sigmoidf_(float x) { return rcpf(1.f + __expf(-x)); }
; template <bool FINAL>
; DI void lru_unit(KA a, int l, int unit, LAS unsigned char* lds) {
;     ...
; #pragma unroll
;         for (int mb = 0; mb < 2; ++mb) {
;             float pp = 1.f, hh = 0.f;
; #pragma unroll
;             for (int i = 0; i < 16; ++i) {
;                 const int t = 32 * mb + 16 * h + i;
;                 const float rg = sigmoidf_(ar[mb][i] + ba_), ig = sigmoidf_(ai[mb][i] + bx_);
;                 const float la = c8 * rg;
;                 float av = __expf(la), mult = __builtin_amdgcn_sqrtf(fmaxf(1.f - av * av, 0.f));
;                 const float xcv = bf2f(xc[t * 72 + cl]);
;                 float bt = mult * ig * xcv;
;                 if (u.prompt && u.c == 0 && t == 0) { av = 0.f; bt = ig * xcv; }
;                 if (t >= nvalid) { av = 1.f; bt = 0.f; }
;                 hh = av * hh + bt; pp *= av;
;                 ar[mb][i] = pp; ai[mb][i] = hh;
;             }
	v_lshlrev_b32_e32 v62, 16, v188
	v_mul_f32_e32 v180, v180, v181
	v_mul_f32_e32 v62, v180, v62
	v_fma_f32 v180, -v16, v16, 1.0
	v_add_f32_e32 v0, 1.0, v0
	v_max_f32_e32 v180, 0, v180
	v_rcp_f32_e32 v0, v0
	v_sqrt_f32_e32 v180, v180
	v_add_f32_e32 v1, v1, v176
	v_mul_f32_e32 v17, v17, v178
	v_mul_f32_e32 v1, 0xbfb8aa3b, v1
	v_mul_f32_e32 v17, 0x3fb8aa3b, v17
	v_exp_f32_e32 v1, v1
	v_exp_f32_e32 v17, v17
	ds_read_u16 v181, v179 offset:4464
	ds_read_u16 v182, v179 offset:4608
	ds_read_u16 v183, v179 offset:4752
	ds_read_u16 v184, v179 offset:4896
	ds_read_u16 v185, v179 offset:5040
	ds_read_u16 v186, v179 offset:5184
	ds_read_u16 v187, v179 offset:5328
	ds_read_u16 v188, v179 offset:5472
	s_waitcnt lgkmcnt(7)
	v_lshlrev_b32_e32 v181, 16, v181
	v_mul_f32_e32 v0, v0, v180
	v_mul_f32_e32 v0, v0, v181
	v_cndmask_b32_e64 v180, 0, v0, s[58:59]
	v_add_f32_e32 v0, 1.0, v1
	v_fma_f32 v1, -v17, v17, 1.0
	v_max_f32_e32 v1, 0, v1
	v_rcp_f32_e32 v0, v0
	v_sqrt_f32_e32 v1, v1
	v_add_f32_e32 v2, v2, v176
	v_mul_f32_e32 v2, 0xbfb8aa3b, v2
	v_exp_f32_e32 v2, v2
	v_mul_f32_e32 v0, v0, v1
	v_add_f32_e32 v1, v18, v177
	v_mul_f32_e32 v1, 0xbfb8aa3b, v1
	v_exp_f32_e32 v1, v1
	v_cndmask_b32_e64 v181, 1.0, v16, s[58:59]
	s_waitcnt lgkmcnt(6)
	v_lshlrev_b32_e32 v16, 16, v182
	v_mul_f32_e32 v0, v0, v16
	v_add_f32_e32 v1, 1.0, v1
	v_rcp_f32_e32 v1, v1
	v_fmac_f32_e32 v180, 0, v181
	v_cndmask_b32_e64 v18, 0, v0, s[60:61]
	v_cndmask_b32_e64 v0, 1.0, v17, s[60:61]
	v_mul_f32_e32 v1, v1, v178
	v_mul_f32_e32 v1, 0x3fb8aa3b, v1
	v_exp_f32_e32 v1, v1
	v_fmac_f32_e32 v18, v0, v180
	v_mul_f32_e32 v182, v181, v0
	v_add_f32_e32 v0, 1.0, v2
	v_fma_f32 v2, -v1, v1, 1.0
	v_max_f32_e32 v2, 0, v2
	v_rcp_f32_e32 v0, v0
	v_sqrt_f32_e32 v2, v2
	v_add_f32_e32 v17, v19, v177
	v_mul_f32_e32 v17, 0xbfb8aa3b, v17
	v_exp_f32_e32 v17, v17
	s_waitcnt lgkmcnt(5)
	v_lshlrev_b32_e32 v16, 16, v183
	v_mul_f32_e32 v0, v0, v2
	v_mul_f32_e32 v0, v0, v16
	v_cndmask_b32_e64 v19, 0, v0, s[62:63]
	v_add_f32_e32 v0, 1.0, v17
	v_rcp_f32_e32 v0, v0
	v_add_f32_e32 v2, v3, v176
	v_mul_f32_e32 v2, 0xbfb8aa3b, v2
	v_exp_f32_e32 v2, v2
	v_mul_f32_e32 v0, v0, v178
	v_mul_f32_e32 v0, 0x3fb8aa3b, v0
	v_exp_f32_e32 v0, v0
	v_add_f32_e32 v2, 1.0, v2
	v_rcp_f32_e32 v2, v2
	v_cndmask_b32_e64 v1, 1.0, v1, s[62:63]
	v_fma_f32 v3, -v0, v0, 1.0
	v_max_f32_e32 v3, 0, v3
	v_sqrt_f32_e32 v3, v3
	v_fmac_f32_e32 v19, v1, v18
	v_mul_f32_e32 v183, v1, v182
	s_waitcnt lgkmcnt(4)
	v_lshlrev_b32_e32 v1, 16, v184
	v_mul_f32_e32 v2, v2, v3
	v_mul_f32_e32 v1, v2, v1
	v_add_f32_e32 v2, v20, v177
	v_mul_f32_e32 v2, 0xbfb8aa3b, v2
	v_exp_f32_e32 v2, v2
	v_cndmask_b32_e64 v20, 0, v1, s[64:65]
	v_cndmask_b32_e64 v0, 1.0, v0, s[64:65]
	v_fmac_f32_e32 v20, v0, v19
	v_add_f32_e32 v1, 1.0, v2
	v_rcp_f32_e32 v1, v1
	v_add_f32_e32 v2, v4, v176
	v_mul_f32_e32 v2, 0xbfb8aa3b, v2
	v_exp_f32_e32 v2, v2
	v_mul_f32_e32 v1, v1, v178
	v_mul_f32_e32 v1, 0x3fb8aa3b, v1
	v_exp_f32_e32 v1, v1
	v_mul_f32_e32 v184, v0, v183
	v_add_f32_e32 v0, 1.0, v2
	v_rcp_f32_e32 v0, v0
	v_fma_f32 v2, -v1, v1, 1.0
	v_max_f32_e32 v2, 0, v2
	v_sqrt_f32_e32 v2, v2
	v_add_f32_e32 v4, v21, v177
	v_mul_f32_e32 v4, 0xbfb8aa3b, v4
	v_exp_f32_e32 v4, v4
	s_waitcnt lgkmcnt(3)
	v_lshlrev_b32_e32 v3, 16, v185
	v_mul_f32_e32 v0, v0, v2
	v_mul_f32_e32 v0, v0, v3
	v_cndmask_b32_e64 v21, 0, v0, s[66:67]
	v_add_f32_e32 v0, 1.0, v4
	v_rcp_f32_e32 v0, v0
	v_add_f32_e32 v2, v5, v176
	v_mul_f32_e32 v2, 0xbfb8aa3b, v2
	v_exp_f32_e32 v2, v2
	v_mul_f32_e32 v0, v0, v178
	v_mul_f32_e32 v0, 0x3fb8aa3b, v0
	v_exp_f32_e32 v0, v0
	v_add_f32_e32 v2, 1.0, v2
	v_rcp_f32_e32 v2, v2
	v_cndmask_b32_e64 v1, 1.0, v1, s[66:67]
	v_fma_f32 v3, -v0, v0, 1.0
	v_max_f32_e32 v3, 0, v3
	v_sqrt_f32_e32 v3, v3
	v_fmac_f32_e32 v21, v1, v20
	v_mul_f32_e32 v185, v1, v184
	s_waitcnt lgkmcnt(2)
	v_lshlrev_b32_e32 v1, 16, v186
	v_mul_f32_e32 v2, v2, v3
	v_mul_f32_e32 v1, v2, v1
	v_add_f32_e32 v2, v22, v177
	v_mul_f32_e32 v2, 0xbfb8aa3b, v2
	v_exp_f32_e32 v2, v2
	v_cndmask_b32_e64 v22, 0, v1, s[68:69]
	v_cndmask_b32_e64 v0, 1.0, v0, s[68:69]
	v_fmac_f32_e32 v22, v0, v21
	v_add_f32_e32 v1, 1.0, v2
	v_rcp_f32_e32 v1, v1
	v_add_f32_e32 v2, v6, v176
	v_mul_f32_e32 v2, 0xbfb8aa3b, v2
	v_exp_f32_e32 v2, v2
	v_mul_f32_e32 v1, v1, v178
	v_mul_f32_e32 v1, 0x3fb8aa3b, v1
	v_exp_f32_e32 v1, v1
	v_mul_f32_e32 v186, v0, v185
	v_add_f32_e32 v0, 1.0, v2
	v_rcp_f32_e32 v0, v0
	v_fma_f32 v2, -v1, v1, 1.0
	v_max_f32_e32 v2, 0, v2
	v_sqrt_f32_e32 v2, v2
	v_add_f32_e32 v4, v23, v177
	v_mul_f32_e32 v4, 0xbfb8aa3b, v4
	v_exp_f32_e32 v4, v4
	s_waitcnt lgkmcnt(1)
	v_lshlrev_b32_e32 v3, 16, v187
	v_mul_f32_e32 v0, v0, v2
	v_mul_f32_e32 v0, v0, v3
	v_cndmask_b32_e64 v23, 0, v0, s[70:71]
	v_add_f32_e32 v0, 1.0, v4
	v_rcp_f32_e32 v0, v0
	v_add_f32_e32 v2, v7, v176
	v_mul_f32_e32 v2, 0xbfb8aa3b, v2
	v_exp_f32_e32 v2, v2
	v_mul_f32_e32 v0, v0, v178
	v_mul_f32_e32 v0, 0x3fb8aa3b, v0
	v_exp_f32_e32 v0, v0
	v_add_f32_e32 v2, 1.0, v2
	v_rcp_f32_e32 v2, v2
	v_cndmask_b32_e64 v1, 1.0, v1, s[70:71]
	v_fma_f32 v3, -v0, v0, 1.0
	v_max_f32_e32 v3, 0, v3
	v_sqrt_f32_e32 v3, v3
	v_fmac_f32_e32 v23, v1, v22
	v_mul_f32_e32 v187, v1, v186
	s_waitcnt lgkmcnt(0)
	v_lshlrev_b32_e32 v1, 16, v188
	v_mul_f32_e32 v2, v2, v3
	v_mul_f32_e32 v1, v2, v1
	v_add_f32_e32 v2, v24, v177
	v_mul_f32_e32 v2, 0xbfb8aa3b, v2
	v_exp_f32_e32 v2, v2
	v_cndmask_b32_e64 v24, 0, v1, s[72:73]
	v_cndmask_b32_e64 v0, 1.0, v0, s[72:73]
	v_fmac_f32_e32 v24, v0, v23
	v_add_f32_e32 v1, 1.0, v2
	v_rcp_f32_e32 v1, v1
	v_add_f32_e32 v2, v8, v176
	v_mul_f32_e32 v2, 0xbfb8aa3b, v2
	v_exp_f32_e32 v2, v2
	v_mul_f32_e32 v1, v1, v178
	v_mul_f32_e32 v1, 0x3fb8aa3b, v1
	v_exp_f32_e32 v1, v1
	v_mul_f32_e32 v188, v0, v187
	v_add_f32_e32 v0, 1.0, v2
	v_rcp_f32_e32 v0, v0
	v_fma_f32 v2, -v1, v1, 1.0
	v_max_f32_e32 v2, 0, v2
	v_sqrt_f32_e32 v2, v2
	v_add_f32_e32 v25, v25, v177
	v_mul_f32_e32 v25, 0xbfb8aa3b, v25
	ds_read_u16 v3, v179 offset:5616
	ds_read_u16 v4, v179 offset:5760
	ds_read_u16 v5, v179 offset:5904
	ds_read_u16 v6, v179 offset:6048
	ds_read_u16 v7, v179 offset:6192
	ds_read_u16 v8, v179 offset:6336
	ds_read_u16 v16, v179 offset:6480
	ds_read_u16 v17, v179 offset:6624
	v_exp_f32_e32 v179, v25
	s_waitcnt lgkmcnt(7)
; DI float bf2f(unsigned v) { return __uint_as_float(v << 16); }
; DI float sigmoidf_(float x) { return rcpf(1.f + __expf(-x)); }
; template <bool FINAL>
; DI void lru_unit(KA a, int l, int unit, LAS unsigned char* lds) {
;     ...
;         for (int mb = 0; mb < 2; ++mb) {
;             float pp = 1.f, hh = 0.f;
; #pragma unroll
;             for (int i = 0; i < 16; ++i) {
;                 const int t = 32 * mb + 16 * h + i;
;                 const float rg = sigmoidf_(ar[mb][i] + ba_), ig = sigmoidf_(ai[mb][i] + bx_);
;                 const float la = c8 * rg;
;                 float av = __expf(la), mult = __builtin_amdgcn_sqrtf(fmaxf(1.f - av * av, 0.f));
;                 const float xcv = bf2f(xc[t * 72 + cl]);
;                 float bt = mult * ig * xcv;
;                 if (u.prompt && u.c == 0 && t == 0) { av = 0.f; bt = ig * xcv; }
;                 if (t >= nvalid) { av = 1.f; bt = 0.f; }
;                 hh = av * hh + bt; pp *= av;
;                 ar[mb][i] = pp; ai[mb][i] = hh;
;             }
;         }
;         const float PA = ar[0][15], HA = ai[0][15], PB = ar[1][15], HB = ai[1][15];
;         const float PAo = __shfl_xor(PA, 32), HAo = __shfl_xor(HA, 32), PBo = __shfl_xor(PB, 32), HBo = __shfl_xor(HB, 32);
;         const float P0 = h ? PAo : PA, H0 = h ? HAo : HA, P1 = h ? PA : PAo, H1 = h ? HA : HAo;
;         const float P2 = h ? PBo : PB, H2 = h ? HBo : HB, P3 = h ? PB : PBo, H3 = h ? HB : HBo;
;         {
;             if (u.prompt) {
;                 unsigned long long* ls = (unsigned long long*)(a->ws + WS_LSUM);
;                 unsigned* lf = (unsigned*)(a->ws + WS_LFLAG);
;                 const unsigned epoch = (unsigned)l + 1u;
;                 if (u.c < NCH - 1) {
;                     const float Pt = P0 * P1 * P2 * P3, Ht = ((H0 * P1 + H1) * P2 + H2) * P3 + H3;
;                     if (h == 0) __hip_atomic_store(ls + (size_t)unit * DLRU + chn, (unsigned long long)__float_as_uint(Pt) | ((unsigned long long)__float_as_uint(Ht) << 32), __ATOMIC_RELAXED, __HIP_MEMORY_SCOPE_AGENT);
	v_lshlrev_b32_e32 v3, 16, v3
	v_mul_f32_e32 v0, v0, v2
	v_mul_f32_e32 v0, v0, v3
	v_cndmask_b32_e64 v25, 0, v0, s[74:75]
	v_add_f32_e32 v0, 1.0, v179
	v_rcp_f32_e32 v0, v0
	v_add_f32_e32 v2, v9, v176
	v_mul_f32_e32 v2, 0xbfb8aa3b, v2
	v_exp_f32_e32 v2, v2
	v_mul_f32_e32 v0, v0, v178
	v_mul_f32_e32 v0, 0x3fb8aa3b, v0
	v_exp_f32_e32 v0, v0
	v_add_f32_e32 v2, 1.0, v2
	v_rcp_f32_e32 v2, v2
	v_cndmask_b32_e64 v1, 1.0, v1, s[74:75]
	v_fma_f32 v3, -v0, v0, 1.0
	v_max_f32_e32 v3, 0, v3
	v_sqrt_f32_e32 v3, v3
	v_fmac_f32_e32 v25, v1, v24
	v_mul_f32_e32 v179, v1, v188
	s_waitcnt lgkmcnt(6)
	v_lshlrev_b32_e32 v1, 16, v4
	v_mul_f32_e32 v2, v2, v3
	v_mul_f32_e32 v1, v2, v1
	v_add_f32_e32 v2, v26, v177
	v_mul_f32_e32 v2, 0xbfb8aa3b, v2
	v_exp_f32_e32 v2, v2
	v_cndmask_b32_e64 v26, 0, v1, s[76:77]
	v_cndmask_b32_e64 v0, 1.0, v0, s[76:77]
	v_fmac_f32_e32 v26, v0, v25
	v_add_f32_e32 v1, 1.0, v2
	v_rcp_f32_e32 v1, v1
	v_add_f32_e32 v2, v10, v176
	v_mul_f32_e32 v2, 0xbfb8aa3b, v2
	v_exp_f32_e32 v2, v2
	v_mul_f32_e32 v1, v1, v178
	v_mul_f32_e32 v1, 0x3fb8aa3b, v1
	v_exp_f32_e32 v1, v1
	v_mul_f32_e32 v189, v0, v179
	v_add_f32_e32 v0, 1.0, v2
	v_rcp_f32_e32 v0, v0
	v_fma_f32 v2, -v1, v1, 1.0
	v_max_f32_e32 v2, 0, v2
	v_sqrt_f32_e32 v2, v2
	v_add_f32_e32 v4, v27, v177
	v_mul_f32_e32 v4, 0xbfb8aa3b, v4
	v_exp_f32_e32 v4, v4
	s_waitcnt lgkmcnt(5)
	v_lshlrev_b32_e32 v3, 16, v5
	v_mul_f32_e32 v0, v0, v2
	v_mul_f32_e32 v0, v0, v3
	v_cndmask_b32_e64 v27, 0, v0, s[78:79]
	v_add_f32_e32 v0, 1.0, v4
	v_rcp_f32_e32 v0, v0
	v_add_f32_e32 v2, v11, v176
	v_mul_f32_e32 v2, 0xbfb8aa3b, v2
	v_exp_f32_e32 v2, v2
	v_mul_f32_e32 v0, v0, v178
	v_mul_f32_e32 v0, 0x3fb8aa3b, v0
	v_exp_f32_e32 v0, v0
	v_add_f32_e32 v2, 1.0, v2
	v_rcp_f32_e32 v2, v2
	v_cndmask_b32_e64 v1, 1.0, v1, s[78:79]
	v_fma_f32 v3, -v0, v0, 1.0
	v_max_f32_e32 v3, 0, v3
	v_sqrt_f32_e32 v3, v3
	v_fmac_f32_e32 v27, v1, v26
	v_mul_f32_e32 v190, v1, v189
	s_waitcnt lgkmcnt(4)
	v_lshlrev_b32_e32 v1, 16, v6
	v_mul_f32_e32 v2, v2, v3
	v_mul_f32_e32 v1, v2, v1
	v_add_f32_e32 v2, v28, v177
	v_mul_f32_e32 v2, 0xbfb8aa3b, v2
	v_exp_f32_e32 v2, v2
	v_cndmask_b32_e64 v28, 0, v1, s[80:81]
	v_cndmask_b32_e64 v0, 1.0, v0, s[80:81]
	v_fmac_f32_e32 v28, v0, v27
	v_add_f32_e32 v1, 1.0, v2
	v_rcp_f32_e32 v1, v1
	v_add_f32_e32 v2, v12, v176
	v_mul_f32_e32 v2, 0xbfb8aa3b, v2
	v_exp_f32_e32 v2, v2
	v_mul_f32_e32 v1, v1, v178
	v_mul_f32_e32 v1, 0x3fb8aa3b, v1
	v_exp_f32_e32 v1, v1
	v_mul_f32_e32 v191, v0, v190
	v_add_f32_e32 v0, 1.0, v2
	v_rcp_f32_e32 v0, v0
	v_fma_f32 v2, -v1, v1, 1.0
	v_max_f32_e32 v2, 0, v2
	v_sqrt_f32_e32 v2, v2
	v_add_f32_e32 v4, v29, v177
	v_mul_f32_e32 v4, 0xbfb8aa3b, v4
	v_exp_f32_e32 v4, v4
	s_waitcnt lgkmcnt(3)
	v_lshlrev_b32_e32 v3, 16, v7
	v_mul_f32_e32 v0, v0, v2
	v_mul_f32_e32 v0, v0, v3
	v_cndmask_b32_e64 v29, 0, v0, s[82:83]
	v_add_f32_e32 v0, 1.0, v4
	v_rcp_f32_e32 v0, v0
	v_add_f32_e32 v2, v13, v176
	v_mul_f32_e32 v2, 0xbfb8aa3b, v2
	v_exp_f32_e32 v2, v2
	v_mul_f32_e32 v0, v0, v178
	v_mul_f32_e32 v0, 0x3fb8aa3b, v0
	v_exp_f32_e32 v0, v0
	v_add_f32_e32 v2, 1.0, v2
	v_rcp_f32_e32 v2, v2
	v_cndmask_b32_e64 v1, 1.0, v1, s[82:83]
	v_fma_f32 v3, -v0, v0, 1.0
	v_max_f32_e32 v3, 0, v3
	v_sqrt_f32_e32 v3, v3
	v_fmac_f32_e32 v29, v1, v28
	v_mul_f32_e32 v192, v1, v191
	s_waitcnt lgkmcnt(2)
	v_lshlrev_b32_e32 v1, 16, v8
	v_mul_f32_e32 v2, v2, v3
	v_mul_f32_e32 v1, v2, v1
	v_add_f32_e32 v2, v30, v177
	v_mul_f32_e32 v2, 0xbfb8aa3b, v2
	v_exp_f32_e32 v2, v2
	v_cndmask_b32_e64 v30, 0, v1, s[84:85]
	v_cndmask_b32_e64 v0, 1.0, v0, s[84:85]
	v_fmac_f32_e32 v30, v0, v29
	v_add_f32_e32 v1, 1.0, v2
	v_rcp_f32_e32 v1, v1
	v_add_f32_e32 v2, v14, v176
	v_mul_f32_e32 v2, 0xbfb8aa3b, v2
	v_exp_f32_e32 v2, v2
	v_mul_f32_e32 v1, v1, v178
	v_mul_f32_e32 v1, 0x3fb8aa3b, v1
	v_exp_f32_e32 v1, v1
	v_mul_f32_e32 v193, v0, v192
	v_add_f32_e32 v0, 1.0, v2
	v_rcp_f32_e32 v0, v0
	v_fma_f32 v2, -v1, v1, 1.0
	v_max_f32_e32 v2, 0, v2
	v_sqrt_f32_e32 v2, v2
	v_add_f32_e32 v4, v31, v177
	v_mul_f32_e32 v4, 0xbfb8aa3b, v4
	v_exp_f32_e32 v4, v4
	s_waitcnt lgkmcnt(1)
	v_lshlrev_b32_e32 v3, 16, v16
	v_mul_f32_e32 v0, v0, v2
	v_mul_f32_e32 v0, v0, v3
	v_cndmask_b32_e64 v31, 0, v0, s[86:87]
	v_add_f32_e32 v0, 1.0, v4
	v_rcp_f32_e32 v0, v0
	v_add_f32_e32 v2, v15, v176
	v_mul_f32_e32 v2, 0xbfb8aa3b, v2
	v_exp_f32_e32 v2, v2
	v_mul_f32_e32 v0, v0, v178
	v_mul_f32_e32 v0, 0x3fb8aa3b, v0
	v_exp_f32_e32 v0, v0
	v_add_f32_e32 v2, 1.0, v2
	v_rcp_f32_e32 v2, v2
	v_cndmask_b32_e64 v1, 1.0, v1, s[86:87]
	v_fma_f32 v3, -v0, v0, 1.0
	v_max_f32_e32 v3, 0, v3
	v_sqrt_f32_e32 v3, v3
	v_fmac_f32_e32 v31, v1, v30
	v_mul_f32_e32 v176, v1, v193
	s_waitcnt lgkmcnt(0)
	v_lshlrev_b32_e32 v1, 16, v17
	v_mul_f32_e32 v2, v2, v3
	v_mul_f32_e32 v1, v2, v1
	v_cndmask_b32_e64 v62, 0, v62, s[56:57]
	v_cndmask_b32_e64 v63, 1.0, v63, s[56:57]
	v_cndmask_b32_e64 v177, 0, v1, s[88:89]
	v_cndmask_b32_e64 v0, 1.0, v0, s[88:89]
	v_fmac_f32_e32 v62, v63, v61
	v_mul_f32_e32 v63, v63, v47
	v_fmac_f32_e32 v177, v0, v31
	v_mul_f32_e32 v178, v0, v176
.Llru_scan_end:
	ds_bpermute_b32 v195, v125, v63
	ds_bpermute_b32 v196, v125, v62
	ds_bpermute_b32 v197, v125, v178
	ds_bpermute_b32 v194, v125, v177
	v_readlane_b32 s4, v255, 14
	v_readlane_b32 s5, v255, 15
	s_andn2_b64 vcc, exec, s[4:5]
	s_cbranch_vccnz .LBB0_1029
	v_readlane_b32 s4, v255, 22
	v_readlane_b32 s5, v255, 23
	s_andn2_b64 vcc, exec, s[4:5]
	s_cbranch_vccnz .LBB0_1022
	s_and_saveexec_b64 s[4:5], s[8:9]
	s_cbranch_execz .LBB0_1019
	s_waitcnt lgkmcnt(2)
	v_fma_f32 v0, v62, v195, v196
	v_fma_f32 v0, v178, v0, v177
	s_waitcnt lgkmcnt(0)
	v_fma_f32 v1, v0, v197, v194
	v_mul_f32_e32 v0, v63, v195
	v_readlane_b32 s6, v255, 24
	v_mul_f32_e32 v0, v178, v0
	v_readlane_b32 s7, v255, 25
	v_mul_f32_e32 v0, v0, v197
	s_nop 0
	v_lshl_add_u64 v[2:3], v[122:123], 3, s[6:7]
	global_store_dwordx2 v[2:3], v[0:1], off sc1
